# code placement: GU K-loop head moved to 0 mod 8 bytes (one unreachable s_nop pad)
# speedup vs baseline: 1.0013x; 1.0013x over previous
; #define PG8_STAGE(bufoff, gbase, voff) do { _Pragma("unroll") for (int _i = 0; _i < 2; ++_i) \
;         __builtin_amdgcn_global_load_lds((const unsigned*)((const char*)(gbase) + (voff)[_i]), (PG8_LAS unsigned*)(lds + (bufoff) + ldsw + _i * 8192), 16, 0, 0); } while (0)
; #define PG8_LDA(dst, b, h) do { _Pragma("unroll") for (int m = 0; m < 4; ++m) _Pragma("unroll") for (int k = 0; k < 2; ++k) dst[m][k] = *(const PG8_LAS bf16x8*)(lds + PG8_SA(b, h) + aoff + m * 2048 + k * 1024); } while (0)
; #define PG8_LDB(dst, b, h) do { _Pragma("unroll") for (int n = 0; n < 2; ++n) _Pragma("unroll") for (int k = 0; k < 2; ++k) dst[n][k] = *(const PG8_LAS bf16x8*)(lds + PG8_SB(b, h) + boff + n * 2048 + k * 1024); } while (0)
; #define PG8_WAIT_V(n) asm volatile("s_waitcnt vmcnt(" #n ")" ::: "memory")
; #define PG8_WAIT_L(n) asm volatile("s_waitcnt lgkmcnt(" #n ")" ::: "memory")
; template <class Epi, class Sched, bool ALIGN_EPI = false, bool SP2 = false>
; __device__ __forceinline__ void gemm_phase(PG8_LAS unsigned char* lds, const Gemm g, const Sched& S, const Epi& E, const int wave_s) {
;     ...
;         const bool has_next = S.next(ui + 1, nxt);
;         const char* nA = has_next ? (const char*)g.A + (size_t)nxt.pm * tstep + (size_t)nxt.k0 * kstep : cA; const char* nB = has_next ? (const char*)g.Bt + (size_t)nxt.pn * tstep + (size_t)nxt.k0 * kstep : cB;
;         const int clen = cur.len;
;         for (int t = 0; t < clen; t += 2) {
;             const bool last = (t == clen - 2);
;             const char* a1 = cA + (size_t)(t + 1) * kstep;
;             const char* a2 = last ? nA : cA + (size_t)(t + 2) * kstep; const char* b2 = last ? nB : cB + (size_t)(t + 2) * kstep;
;             const char* a3 = a2 + kstep; const char* b3 = b2 + kstep;
;             if (last && has_next) S.a_ready(nxt);
;             if constexpr (SP2) {
;             PG8_LDB(B0, 0, 0); PG8_LDB(B1, 0, 1); PG8_SCHED; PG8_LDA(At, 0, 0); PG8_STAGE(PG8_SA(1, 1), a1 + hstep, voffA);
;             PG8_WAIT_V(8); PG8_WAIT_L(0); PG8_BAR; PG8_MMA(0, 0, At, B0); PG8_MMA(0, 1, At, B1); PG8_BAR; PG8_SCHED;
;             PG8_LDA(At, 0, 1); PG8_STAGE(PG8_SB(0, 0), b2, voffB); PG8_STAGE(PG8_SB(0, 1), b2 + hstep, voffB); PG8_STAGE(PG8_SA(0, 0), a2, voffA);
;             PG8_WAIT_V(8); PG8_WAIT_L(0); PG8_BAR; PG8_MMA(1, 0, At, B0); PG8_MMA(1, 1, At, B1); PG8_BAR; PG8_SCHED;
.Lgum_522:
	s_ashr_i32 s19, s18, 31
	s_lshl_b64 s[20:21], s[18:19], 19
	s_add_u32 s20, s28, s20
	s_addc_u32 s21, s29, s21
	s_and_b64 s[22:23], s[6:7], exec
	s_cselect_b32 s19, s21, s25
	s_cselect_b32 s46, s20, s24
	s_ashr_i32 s17, s16, 31
	s_lshl_b64 s[22:23], s[16:17], 19
	s_add_u32 s22, s30, s22
	s_addc_u32 s23, s31, s23
	s_and_b64 s[100:101], s[6:7], exec
	s_cselect_b32 s17, s23, s49
	s_cselect_b32 s47, s22, s48
	s_waitcnt vmcnt(8)
	s_waitcnt lgkmcnt(0)
	s_barrier
	s_setprio 1
	s_waitcnt lgkmcnt(0)
	v_mfma_f32_16x16x32_bf16 v[124:127], v[140:143], v[190:193], 0
	v_mfma_f32_16x16x32_bf16 v[116:119], v[154:157], v[190:193], 0
	v_mfma_f32_16x16x32_bf16 v[108:111], v[140:143], v[214:217], 0
	v_mfma_f32_16x16x32_bf16 v[100:103], v[154:157], v[214:217], 0
	v_mfma_f32_16x16x32_bf16 v[92:95], v[140:143], v[222:225], 0
	v_mfma_f32_16x16x32_bf16 v[84:87], v[154:157], v[222:225], 0
	v_mfma_f32_16x16x32_bf16 v[76:79], v[140:143], v[230:233], 0
	v_mfma_f32_16x16x32_bf16 v[68:71], v[154:157], v[230:233], 0
	v_mfma_f32_16x16x32_bf16 v[124:127], v[150:153], v[210:213], v[124:127]
	v_mfma_f32_16x16x32_bf16 v[116:119], v[158:161], v[210:213], v[116:119]
	v_mfma_f32_16x16x32_bf16 v[108:111], v[150:153], v[218:221], v[108:111]
	v_mfma_f32_16x16x32_bf16 v[100:103], v[158:161], v[218:221], v[100:103]
	v_mfma_f32_16x16x32_bf16 v[92:95], v[150:153], v[226:229], v[92:95]
	v_mfma_f32_16x16x32_bf16 v[84:87], v[158:161], v[226:229], v[84:87]
	v_mfma_f32_16x16x32_bf16 v[76:79], v[150:153], v[234:237], v[76:79]
	v_mfma_f32_16x16x32_bf16 v[68:71], v[158:161], v[234:237], v[68:71]
	s_setprio 0
	s_setprio 1
	v_mfma_f32_16x16x32_bf16 v[120:123], v[174:177], v[190:193], 0
	v_mfma_f32_16x16x32_bf16 v[112:115], v[182:185], v[190:193], 0
	v_mfma_f32_16x16x32_bf16 v[104:107], v[174:177], v[214:217], 0
	v_mfma_f32_16x16x32_bf16 v[96:99], v[182:185], v[214:217], 0
	v_mfma_f32_16x16x32_bf16 v[88:91], v[174:177], v[222:225], 0
	v_mfma_f32_16x16x32_bf16 v[80:83], v[182:185], v[222:225], 0
	v_mfma_f32_16x16x32_bf16 v[72:75], v[174:177], v[230:233], 0
	v_mfma_f32_16x16x32_bf16 v[64:67], v[182:185], v[230:233], 0
	v_mfma_f32_16x16x32_bf16 v[120:123], v[178:181], v[210:213], v[120:123]
	v_mfma_f32_16x16x32_bf16 v[112:115], v[186:189], v[210:213], v[112:115]
	v_mfma_f32_16x16x32_bf16 v[104:107], v[178:181], v[218:221], v[104:107]
	v_mfma_f32_16x16x32_bf16 v[96:99], v[186:189], v[218:221], v[96:99]
	v_mfma_f32_16x16x32_bf16 v[88:91], v[178:181], v[226:229], v[88:91]
	v_mfma_f32_16x16x32_bf16 v[80:83], v[186:189], v[226:229], v[80:83]
	v_mfma_f32_16x16x32_bf16 v[72:75], v[178:181], v[234:237], v[72:75]
	v_mfma_f32_16x16x32_bf16 v[64:67], v[186:189], v[234:237], v[64:67]
	s_setprio 0
	s_barrier
	s_add_i32 s51, s51, s34
	v_lshl_add_u64 v[194:195], s[2:3], 0, v[128:129]
	s_mov_b32 m0, s51
	ds_read_b128 v[190:193], v148 offset:16384
	ds_read_b128 v[210:213], v148 offset:17408
	ds_read_b128 v[214:217], v148 offset:18432
	ds_read_b128 v[218:221], v148 offset:19456
	ds_read_b128 v[222:225], v148 offset:20480
	ds_read_b128 v[226:229], v148 offset:21504
	ds_read_b128 v[230:233], v148 offset:22528
	ds_read_b128 v[234:237], v148 offset:23552
	global_load_lds_dwordx4 v[194:195], off
	s_add_i32 m0, s51, 0x2000
	s_add_u32 s52, s2, 0x40000
	v_lshl_add_u64 v[238:239], s[2:3], 0, v[130:131]
	s_addc_u32 s53, s3, 0
	s_add_i32 s51, s54, s34
	global_load_lds_dwordx4 v[238:239], off
	v_lshl_add_u64 v[240:241], s[52:53], 0, v[128:129]
	s_mov_b32 m0, s51
	v_lshl_add_u64 v[242:243], s[26:27], 0, v[132:133]
	global_load_lds_dwordx4 v[240:241], off
	v_lshl_add_u64 v[240:241], s[52:53], 0, v[130:131]
	s_add_i32 m0, s51, 0x2000
	s_nop 0
	global_load_lds_dwordx4 v[240:241], off
	v_lshl_add_u64 v[240:241], s[26:27], 0, v[134:135]
	s_mov_b32 m0, s35
	s_nop 0
	global_load_lds_dwordx4 v[240:241], off
	s_mov_b32 m0, s36
	s_nop 0
	global_load_lds_dwordx4 v[242:243], off
	s_waitcnt vmcnt(8)
	s_waitcnt lgkmcnt(0)
	s_barrier
	s_setprio 1
	s_waitcnt lgkmcnt(0)
	v_mfma_f32_16x16x32_bf16 v[60:63], v[140:143], v[190:193], 0
	v_mfma_f32_16x16x32_bf16 v[52:55], v[154:157], v[190:193], 0
	v_mfma_f32_16x16x32_bf16 v[44:47], v[140:143], v[214:217], 0
	v_mfma_f32_16x16x32_bf16 v[36:39], v[154:157], v[214:217], 0
	v_mfma_f32_16x16x32_bf16 v[28:31], v[140:143], v[222:225], 0
	v_mfma_f32_16x16x32_bf16 v[20:23], v[154:157], v[222:225], 0
	v_mfma_f32_16x16x32_bf16 v[12:15], v[140:143], v[230:233], 0
	v_mfma_f32_16x16x32_bf16 v[4:7], v[154:157], v[230:233], 0
	v_mfma_f32_16x16x32_bf16 v[60:63], v[150:153], v[210:213], v[60:63]
	v_mfma_f32_16x16x32_bf16 v[52:55], v[158:161], v[210:213], v[52:55]
	v_mfma_f32_16x16x32_bf16 v[44:47], v[150:153], v[218:221], v[44:47]
	v_mfma_f32_16x16x32_bf16 v[36:39], v[158:161], v[218:221], v[36:39]
	v_mfma_f32_16x16x32_bf16 v[28:31], v[150:153], v[226:229], v[28:31]
	v_mfma_f32_16x16x32_bf16 v[20:23], v[158:161], v[226:229], v[20:23]
	v_mfma_f32_16x16x32_bf16 v[12:15], v[150:153], v[234:237], v[12:15]
	v_mfma_f32_16x16x32_bf16 v[4:7], v[158:161], v[234:237], v[4:7]
	s_setprio 0
	s_setprio 1
	v_mfma_f32_16x16x32_bf16 v[56:59], v[174:177], v[190:193], 0
	v_mfma_f32_16x16x32_bf16 v[48:51], v[182:185], v[190:193], 0
	v_mfma_f32_16x16x32_bf16 v[40:43], v[174:177], v[214:217], 0
	v_mfma_f32_16x16x32_bf16 v[32:35], v[182:185], v[214:217], 0
	v_mfma_f32_16x16x32_bf16 v[24:27], v[174:177], v[222:225], 0
	v_mfma_f32_16x16x32_bf16 v[16:19], v[182:185], v[222:225], 0
	v_mfma_f32_16x16x32_bf16 v[8:11], v[174:177], v[230:233], 0
	v_mfma_f32_16x16x32_bf16 v[0:3], v[182:185], v[230:233], 0
	v_mfma_f32_16x16x32_bf16 v[56:59], v[178:181], v[210:213], v[56:59]
	v_mfma_f32_16x16x32_bf16 v[48:51], v[186:189], v[210:213], v[48:51]
	v_mfma_f32_16x16x32_bf16 v[40:43], v[178:181], v[218:221], v[40:43]
	v_mfma_f32_16x16x32_bf16 v[32:35], v[186:189], v[218:221], v[32:35]
	v_mfma_f32_16x16x32_bf16 v[24:27], v[178:181], v[226:229], v[24:27]
	v_mfma_f32_16x16x32_bf16 v[16:19], v[186:189], v[226:229], v[16:19]
	v_mfma_f32_16x16x32_bf16 v[8:11], v[178:181], v[234:237], v[8:11]
	v_mfma_f32_16x16x32_bf16 v[0:3], v[186:189], v[234:237], v[0:3]
	s_setprio 0
	s_barrier
	s_branch .Lpeel1_seg3
	s_nop 0
